# second K-loop wait of later P1 tiles also relaxed past the previous epilogue's stores (phase prologue drains fully)
# baseline (speedup 1.0000x reference)
; #define PG8_STAGE(bufoff, gbase, voff) do { _Pragma("unroll") for (int _i = 0; _i < 2; ++_i) \
;         __builtin_amdgcn_global_load_lds((const unsigned*)((const char*)(gbase) + (voff)[_i]), (LAS unsigned*)(lds + (bufoff) + ldsw + _i * 8192), 16, 0, 0); } while (0)
; #define PG8_WAIT_V(n) asm volatile("s_waitcnt vmcnt(" #n ")" ::: "memory")
; #define PG8_BAR __builtin_amdgcn_s_barrier()
; template <class Epi, int AC0, int BC0, int NT0, int AC1, int BC1, int NT1>
; __device__ __forceinline__ void gemm_phase(LAS unsigned char* lds, const Gemm g, const StaticOrder& S, const Epi& E, int tid) {
;     ...
;     for (int i = 0; i < 2; ++i) { int R, C; stage_rc(tid * 16 + i * 8192, R, C); const int Rb = (R & ~31) + perm32(R & 31);
;         voffA[i] = (unsigned)(R * g.lda + C) * 2u; voffB[i] = (unsigned)(Rb * g.ldb + C) * 2u; }
;     const size_t kstep = (size_t)(BK * 2);
;     const size_t hstepA = (size_t)HALF * g.lda * 2, hstepB = (size_t)HALF * g.ldb * 2;
;     const unsigned ldsw = (unsigned)wid * 1024u;
;     const int aoff = lds_byte(wr * 64 + fr, fq * 8), boff = lds_byte(wc * 32 + fr, fq * 8);
;     ...
;     Unit cur, nxt; int ui = 0;
;     if (!S.next(0, cur)) return;
;     f32x4 acc[2][2][4][2];
; #pragma unroll
;     for (int a = 0; a < 2; ++a)
; #pragma unroll
;         for (int b = 0; b < 2; ++b)
; #pragma unroll
;             for (int m = 0; m < 4; ++m)
; #pragma unroll
;                 for (int n = 0; n < 2; ++n) acc[a][b][m][n] = (f32x4){0.f, 0.f, 0.f, 0.f};
;     bf16x8 At[4][2], B0[2][2], B1[2][2];
;     const char* cA = PG8_APTR(cur); const char* cB = PG8_BPTR(cur);
;     PG8_STAGE(PG8_SB(0, 0), cB, voffB); PG8_STAGE(PG8_SB(0, 1), cB + hstepB, voffB); PG8_STAGE(PG8_SA(0, 0), cA, voffA); PG8_STAGE(PG8_SA(0, 1), cA + hstepA, voffA);
;     if (wr == 1) PG8_BAR;
;     PG8_WAIT_V(2); PG8_BAR;
;     PG8_STAGE(PG8_SB(1, 0), cB + kstep, voffB); PG8_STAGE(PG8_SA(1, 0), cA + kstep, voffA); PG8_STAGE(PG8_SB(1, 1), cB + hstepB + kstep, voffB);
;     PG8_WAIT_V(6); PG8_BAR;
.LBB0_114:
	s_mov_b64 s[20:21], 0x80
	s_and_b32 s5, s3, 3
	s_lshl_b32 s9, s4, 6
	s_add_i32 m0, s95, 0x18000
	v_lshl_add_u64 v[6:7], v[6:7], 0, s[20:21]
	v_writelane_b32 v254, s9, 17
	s_lshl_b32 s9, s4, 13
	s_lshl_b32 s11, s5, 12
	s_waitcnt vmcnt(2)
	s_barrier
	global_load_lds_dwordx4 v[6:7], off
	v_lshl_add_u64 v[4:5], v[4:5], 0, s[20:21]
	s_add_i32 m0, s95, 0x1a000
	s_add_i32 s19, s95, 0x8000
	s_add_i32 s46, s95, 0xa000
	global_load_lds_dwordx4 v[4:5], off
	v_lshl_add_u64 v[2:3], v[2:3], 0, s[20:21]
	s_mov_b32 m0, s19
	s_add_u32 s4, s6, 0x40080
	v_writelane_b32 v254, s5, 19
	global_load_lds_dwordx4 v[2:3], off
	v_lshl_add_u64 v[2:3], v[8:9], 0, s[20:21]
	s_mov_b32 m0, s46
	s_addc_u32 s5, s7, 0
	global_load_lds_dwordx4 v[2:3], off
	s_add_i32 m0, s95, 0x1c000
	v_lshl_add_u64 v[2:3], s[4:5], 0, v[166:167]
	global_load_lds_dwordx4 v[2:3], off
	v_lshl_add_u64 v[2:3], s[4:5], 0, v[170:171]
	s_add_i32 m0, s95, 0x1e000
	v_and_b32_e32 v1, 15, v10
	global_load_lds_dwordx4 v[2:3], off
	v_lshrrev_b32_e32 v2, 1, v10
	v_and_b32_e32 v2, 24, v2
	v_lshlrev_b32_e32 v3, 1, v2
	v_lshlrev_b32_e32 v4, 2, v10
	v_lshl_or_b32 v3, v1, 6, v3
	v_and_b32_e32 v4, 32, v4
	s_cmpk_lt_u32 s2, 0x100
	v_bitop3_b32 v6, v3, s9, v4 bitop3:0xde
	v_bitop3_b32 v188, v3, s11, v4 bitop3:0xde
	s_cselect_b64 s[4:5], -1, 0
	s_lshl_b32 s2, s3, 6
	v_lshlrev_b32_e32 v172, 2, v2
	v_lshlrev_b32_e32 v3, 14, v11
	s_and_b32 s24, s2, 64
	v_lshl_add_u64 v[4:5], s[62:63], 0, v[172:173]
	s_mov_b64 s[2:3], 0x100000
	v_and_b32_e32 v3, 0xffff8000, v3
	v_lshl_add_u64 v[174:175], v[4:5], 0, s[2:3]
	v_lshl_add_u32 v3, v12, 11, v3
	v_and_b32_e32 v4, 1, v11
	v_lshl_or_b32 v3, v4, 6, v3
	v_lshl_add_u32 v178, v13, 1, v3
	v_lshlrev_b32_e32 v3, 14, v14
	v_and_b32_e32 v3, 0xffff8000, v3
	s_waitcnt vmcnt(0)
	v_lshl_add_u32 v3, v15, 11, v3
	v_and_b32_e32 v4, 1, v14
	v_lshl_or_b32 v3, v4, 6, v3
	s_add_i32 s94, 0, 0x10000
	s_add_i32 s18, 0, 0x14000
	v_writelane_b32 v254, s4, 21
	s_mov_b32 s25, s17
	v_or_b32_e32 v189, 16, v1
	v_or_b32_e32 v190, 32, v1
	v_or_b32_e32 v191, 48, v1
	v_lshl_add_u64 v[176:177], s[60:61], 0, v[172:173]
	v_mov_b32_e32 v179, v173
	v_lshl_add_u32 v180, v16, 1, v3
	v_mov_b32_e32 v181, v173
	v_mov_b64_e32 v[182:183], 0xaaa
	v_mov_b64_e32 v[184:185], 0xaa9
	v_add_u32_e32 v192, s94, v188
	v_add_u32_e32 v193, s18, v188
	v_add_u32_e32 v194, 0, v6
	v_mov_b32_e32 v195, 0x358637bd
	s_mov_b32 s2, 0x800000
	s_movk_i32 s23, 0x7fff
	s_movk_i32 s92, 0x2a00
	v_lshlrev_b32_e32 v172, 1, v2
	v_mbcnt_hi_u32_b32 v196, -1, v225
	v_mov_b32_e32 v197, 0x3e38aa3b
	s_mov_b32 s14, 0
	s_barrier
	v_writelane_b32 v254, s5, 22
	s_branch .LBB0_117
; #define PG8_STAGE(bufoff, gbase, voff) do { _Pragma("unroll") for (int _i = 0; _i < 2; ++_i) \
;         __builtin_amdgcn_global_load_lds((const unsigned*)((const char*)(gbase) + (voff)[_i]), (LAS unsigned*)(lds + (bufoff) + ldsw + _i * 8192), 16, 0, 0); } while (0)
; #define PG8_LDA(dst, b, h) do { _Pragma("unroll") for (int m = 0; m < 4; ++m) _Pragma("unroll") for (int k = 0; k < 2; ++k) dst[m][k] = *(const LAS bf16x8*)(lds + PG8_SA(b, h) + aoff + m * 2048 + k * 1024); } while (0)
; #define PG8_LDB(dst, b, h) do { _Pragma("unroll") for (int n = 0; n < 2; ++n) _Pragma("unroll") for (int k = 0; k < 2; ++k) dst[n][k] = *(const LAS bf16x8*)(lds + PG8_SB(b, h) + boff + n * 2048 + k * 1024); } while (0)
; #define PG8_MMA(ai, bj, At, Bt) do { __builtin_amdgcn_s_setprio(1); _Pragma("unroll") for (int m = 0; m < 4; ++m) _Pragma("unroll") for (int n = 0; n < 2; ++n) _Pragma("unroll") for (int k = 0; k < 2; ++k) \
;         acc[ai][bj][m][n] = __builtin_amdgcn_mfma_f32_16x16x32_bf16(Bt[n][k], At[m][k], acc[ai][bj][m][n], 0, 0, 0); __builtin_amdgcn_s_setprio(0); } while (0)
; #define PG8_WAIT_V(n) asm volatile("s_waitcnt vmcnt(" #n ")" ::: "memory")
; #define PG8_WAIT_L(n) asm volatile("s_waitcnt lgkmcnt(" #n ")" ::: "memory")
; #define PG8_BAR __builtin_amdgcn_s_barrier()
; #define PG8_SCHED __builtin_amdgcn_sched_barrier(0)
; template <class Epi, int AC0, int BC0, int NT0, int AC1, int BC1, int NT1>
; __device__ __forceinline__ void gemm_phase(LAS unsigned char* lds, const Gemm g, const StaticOrder& S, const Epi& E, int tid) {
;     ...
;             PG8_LDB(B0, 0, 0); PG8_LDB(B1, 0, 1); PG8_SCHED; PG8_LDA(At, 0, 0); PG8_STAGE(PG8_SA(1, 1), a1 + hstepA, voffA);
;             PG8_WAIT_V(8); PG8_WAIT_L(0); PG8_BAR; PG8_MMA(0, 0, At, B0); PG8_MMA(0, 1, At, B1); PG8_BAR; PG8_SCHED;
;             PG8_LDA(At, 0, 1); PG8_STAGE(PG8_SB(0, 0), b2, voffB); PG8_STAGE(PG8_SB(0, 1), b2 + hstepB, voffB); PG8_STAGE(PG8_SA(0, 0), a2, voffA);
;             PG8_WAIT_V(8); PG8_WAIT_L(0); PG8_BAR; PG8_MMA(1, 0, At, B0); PG8_MMA(1, 1, At, B1); PG8_BAR; PG8_SCHED;
.Lpeel_P1:
	ds_read_b128 v[26:29], v192
	ds_read_b128 v[30:33], v192 offset:1024
	ds_read_b128 v[42:45], v192 offset:2048
	ds_read_b128 v[46:49], v192 offset:3072
	ds_read_b128 v[146:149], v193
	ds_read_b128 v[150:153], v193 offset:1024
	ds_read_b128 v[154:157], v193 offset:2048
	ds_read_b128 v[158:161], v193 offset:3072
	s_add_u32 s6, s0, 0xfffc0080
	s_addc_u32 s7, s1, -1
	s_cmp_eq_u32 s27, 12
	s_cselect_b32 s13, s3, s7
	s_cselect_b32 s12, s9, s6
	s_cselect_b32 s7, s11, s22
	s_cselect_b32 s6, s15, s16
	v_lshl_add_u64 v[186:187], s[0:1], 0, v[178:179]
	s_add_i32 m0, s95, 0xc000
	ds_read_b128 v[198:201], v194
	ds_read_b128 v[202:205], v194 offset:1024
	ds_read_b128 v[206:209], v194 offset:2048
	ds_read_b128 v[210:213], v194 offset:3072
	ds_read_b128 v[214:217], v194 offset:4096
	ds_read_b128 v[218:221], v194 offset:5120
	ds_read_b128 v[226:229], v194 offset:6144
	ds_read_b128 v[230:233], v194 offset:7168
	global_load_lds_dwordx4 v[186:187], off
	v_lshl_add_u64 v[186:187], s[0:1], 0, v[180:181]
	s_add_i32 m0, s95, 0xe000
	s_nop 0
	global_load_lds_dwordx4 v[186:187], off
	s_waitcnt vmcnt(24)
	s_waitcnt lgkmcnt(0)
	s_barrier
	s_setprio 1
	s_waitcnt lgkmcnt(0)
	v_mfma_f32_16x16x32_bf16 v[142:145], v[26:29], v[198:201], 0
	v_mfma_f32_16x16x32_bf16 v[138:141], v[42:45], v[198:201], 0
	v_mfma_f32_16x16x32_bf16 v[126:129], v[26:29], v[206:209], 0
	v_mfma_f32_16x16x32_bf16 v[122:125], v[42:45], v[206:209], 0
	v_mfma_f32_16x16x32_bf16 v[110:113], v[26:29], v[214:217], 0
	v_mfma_f32_16x16x32_bf16 v[106:109], v[42:45], v[214:217], 0
	v_mfma_f32_16x16x32_bf16 v[94:97], v[26:29], v[226:229], 0
	v_mfma_f32_16x16x32_bf16 v[90:93], v[42:45], v[226:229], 0
	v_mfma_f32_16x16x32_bf16 v[142:145], v[30:33], v[202:205], v[142:145]
	v_mfma_f32_16x16x32_bf16 v[138:141], v[46:49], v[202:205], v[138:141]
	v_mfma_f32_16x16x32_bf16 v[126:129], v[30:33], v[210:213], v[126:129]
	v_mfma_f32_16x16x32_bf16 v[122:125], v[46:49], v[210:213], v[122:125]
	v_mfma_f32_16x16x32_bf16 v[110:113], v[30:33], v[218:221], v[110:113]
	v_mfma_f32_16x16x32_bf16 v[106:109], v[46:49], v[218:221], v[106:109]
	v_mfma_f32_16x16x32_bf16 v[94:97], v[30:33], v[230:233], v[94:97]
	v_mfma_f32_16x16x32_bf16 v[90:93], v[46:49], v[230:233], v[90:93]
	s_setprio 0
	s_setprio 1
	v_mfma_f32_16x16x32_bf16 v[134:137], v[146:149], v[198:201], 0
	v_mfma_f32_16x16x32_bf16 v[130:133], v[154:157], v[198:201], 0
	v_mfma_f32_16x16x32_bf16 v[118:121], v[146:149], v[206:209], 0
	v_mfma_f32_16x16x32_bf16 v[114:117], v[154:157], v[206:209], 0
	v_mfma_f32_16x16x32_bf16 v[102:105], v[146:149], v[214:217], 0
	v_mfma_f32_16x16x32_bf16 v[98:101], v[154:157], v[214:217], 0
	v_mfma_f32_16x16x32_bf16 v[86:89], v[146:149], v[226:229], 0
	v_mfma_f32_16x16x32_bf16 v[82:85], v[154:157], v[226:229], 0
	v_mfma_f32_16x16x32_bf16 v[134:137], v[150:153], v[202:205], v[134:137]
	v_mfma_f32_16x16x32_bf16 v[130:133], v[158:161], v[202:205], v[130:133]
	v_mfma_f32_16x16x32_bf16 v[118:121], v[150:153], v[210:213], v[118:121]
	v_mfma_f32_16x16x32_bf16 v[114:117], v[158:161], v[210:213], v[114:117]
	v_mfma_f32_16x16x32_bf16 v[102:105], v[150:153], v[218:221], v[102:105]
	v_mfma_f32_16x16x32_bf16 v[98:101], v[158:161], v[218:221], v[98:101]
	v_mfma_f32_16x16x32_bf16 v[86:89], v[150:153], v[230:233], v[86:89]
	v_mfma_f32_16x16x32_bf16 v[82:85], v[158:161], v[230:233], v[82:85]
	s_setprio 0
	s_barrier
	s_add_i32 s29, s94, s47
	v_lshl_add_u64 v[186:187], s[6:7], 0, v[166:167]
	s_mov_b32 m0, s29
	ds_read_b128 v[198:201], v194 offset:16384
	ds_read_b128 v[202:205], v194 offset:17408
	ds_read_b128 v[206:209], v194 offset:18432
	ds_read_b128 v[210:213], v194 offset:19456
	ds_read_b128 v[214:217], v194 offset:20480
	ds_read_b128 v[218:221], v194 offset:21504
	ds_read_b128 v[226:229], v194 offset:22528
	ds_read_b128 v[230:233], v194 offset:23552
	global_load_lds_dwordx4 v[186:187], off
	s_add_i32 m0, s29, 0x2000
	s_add_u32 s36, s6, 0x40000
	v_lshl_add_u64 v[222:223], s[6:7], 0, v[170:171]
	s_addc_u32 s37, s7, 0
	s_add_i32 s29, s18, s47
	global_load_lds_dwordx4 v[222:223], off
	v_lshl_add_u64 v[234:235], s[36:37], 0, v[166:167]
	s_mov_b32 m0, s29
	v_lshl_add_u64 v[236:237], s[12:13], 0, v[168:169]
	global_load_lds_dwordx4 v[234:235], off
	v_lshl_add_u64 v[234:235], s[36:37], 0, v[170:171]
	s_add_i32 m0, s29, 0x2000
	s_nop 0
	global_load_lds_dwordx4 v[234:235], off
	v_lshl_add_u64 v[234:235], s[12:13], 0, v[164:165]
	s_mov_b32 m0, s95
	s_nop 0
	global_load_lds_dwordx4 v[234:235], off
	s_mov_b32 m0, s96
	s_nop 0
	global_load_lds_dwordx4 v[236:237], off
	s_waitcnt vmcnt(24)
	s_waitcnt lgkmcnt(0)
	s_barrier
	s_setprio 1
	s_waitcnt lgkmcnt(0)
	v_mfma_f32_16x16x32_bf16 v[78:81], v[26:29], v[198:201], 0
	v_mfma_f32_16x16x32_bf16 v[74:77], v[42:45], v[198:201], 0
	v_mfma_f32_16x16x32_bf16 v[62:65], v[26:29], v[206:209], 0
	v_mfma_f32_16x16x32_bf16 v[58:61], v[42:45], v[206:209], 0
	v_mfma_f32_16x16x32_bf16 v[38:41], v[26:29], v[214:217], 0
	v_mfma_f32_16x16x32_bf16 v[34:37], v[42:45], v[214:217], 0
	v_mfma_f32_16x16x32_bf16 v[14:17], v[26:29], v[226:229], 0
	v_mfma_f32_16x16x32_bf16 v[10:13], v[42:45], v[226:229], 0
	v_mfma_f32_16x16x32_bf16 v[78:81], v[30:33], v[202:205], v[78:81]
	v_mfma_f32_16x16x32_bf16 v[74:77], v[46:49], v[202:205], v[74:77]
	v_mfma_f32_16x16x32_bf16 v[62:65], v[30:33], v[210:213], v[62:65]
	v_mfma_f32_16x16x32_bf16 v[58:61], v[46:49], v[210:213], v[58:61]
	v_mfma_f32_16x16x32_bf16 v[38:41], v[30:33], v[218:221], v[38:41]
	v_mfma_f32_16x16x32_bf16 v[34:37], v[46:49], v[218:221], v[34:37]
	v_mfma_f32_16x16x32_bf16 v[14:17], v[30:33], v[230:233], v[14:17]
	v_mfma_f32_16x16x32_bf16 v[10:13], v[46:49], v[230:233], v[10:13]
	s_setprio 0
	s_setprio 1
	v_mfma_f32_16x16x32_bf16 v[22:25], v[146:149], v[214:217], 0
	v_mfma_f32_16x16x32_bf16 v[18:21], v[154:157], v[214:217], 0
	v_mfma_f32_16x16x32_bf16 v[6:9], v[146:149], v[226:229], 0
	v_mfma_f32_16x16x32_bf16 v[2:5], v[154:157], v[226:229], 0
	v_mfma_f32_16x16x32_bf16 v[26:29], v[146:149], v[198:201], 0
	v_mfma_f32_16x16x32_bf16 v[30:33], v[154:157], v[198:201], 0
	v_mfma_f32_16x16x32_bf16 v[42:45], v[146:149], v[206:209], 0
	v_mfma_f32_16x16x32_bf16 v[46:49], v[154:157], v[206:209], 0
	v_mfma_f32_16x16x32_bf16 v[22:25], v[150:153], v[218:221], v[22:25]
	v_mfma_f32_16x16x32_bf16 v[18:21], v[158:161], v[218:221], v[18:21]
	v_mfma_f32_16x16x32_bf16 v[6:9], v[150:153], v[230:233], v[6:9]
	v_mfma_f32_16x16x32_bf16 v[2:5], v[158:161], v[230:233], v[2:5]
	v_mfma_f32_16x16x32_bf16 v[26:29], v[150:153], v[202:205], v[26:29]
	v_mfma_f32_16x16x32_bf16 v[30:33], v[158:161], v[202:205], v[30:33]
	v_mfma_f32_16x16x32_bf16 v[42:45], v[150:153], v[210:213], v[42:45]
	v_mfma_f32_16x16x32_bf16 v[46:49], v[158:161], v[210:213], v[46:49]
	s_setprio 0
	s_barrier
	s_branch .Lmid_P1
